# EpiResid dwordx4 stores written through (sc1) so that the out-GEMM barriers find a cleaner L2 (on top of dynamic conversion)
# baseline (speedup 1.0000x reference)
.LBB0_1100:
	s_or_b64 exec, exec, s[30:31]
	s_waitcnt lgkmcnt(0)
	s_barrier
	ds_read_b32 v208, v227
	v_lshlrev_b64 v[206:207], 10, v[202:203]
	s_cmp_lg_u64 s[26:27], 0
	v_lshl_add_u64 v[206:207], v[206:207], 0, v[196:197]
	s_waitcnt vmcnt(0)
	v_lshlrev_b32_e32 v210, 16, v178
	v_and_b32_e32 v211, 0xffff0000, v178
	v_lshlrev_b32_e32 v178, 16, v179
	v_and_b32_e32 v179, 0xffff0000, v179
	v_lshlrev_b32_e32 v212, 16, v180
	v_and_b32_e32 v213, 0xffff0000, v180
	v_lshlrev_b32_e32 v180, 16, v181
	v_and_b32_e32 v181, 0xffff0000, v181
	s_waitcnt lgkmcnt(0)
	v_pk_mul_f32 v[148:149], v[148:149], v[208:209] op_sel_hi:[1,0]
	v_pk_mul_f32 v[146:147], v[146:147], v[208:209] op_sel_hi:[1,0]
	v_pk_mul_f32 v[144:145], v[144:145], v[208:209] op_sel_hi:[1,0]
	v_pk_mul_f32 v[142:143], v[142:143], v[208:209] op_sel_hi:[1,0]
	s_cselect_b64 s[30:31], -1, 0
	s_cmp_eq_u64 s[26:27], 0
	v_lshl_add_u64 v[206:207], v[206:207], 2, s[26:27]
	v_pk_fma_f32 v[148:149], v[116:117], v[148:149], v[178:179]
	v_pk_fma_f32 v[146:147], v[114:115], v[146:147], v[210:211]
	v_pk_fma_f32 v[144:145], v[112:113], v[144:145], v[180:181]
	v_pk_fma_f32 v[142:143], v[110:111], v[142:143], v[212:213]
	s_cbranch_scc1 .LBB0_1169
	global_store_dwordx4 v[206:207], v[146:149], off sc1
	global_store_dwordx4 v[206:207], v[142:145], off offset:16 sc1
	s_cbranch_execnz .LBB0_1103
.LBB0_1102:
	v_cvt_pk_bf16_f32 v178, v146, v147
	v_cvt_pk_bf16_f32 v179, v148, v149
	v_cvt_pk_bf16_f32 v180, v142, v143
	v_cvt_pk_bf16_f32 v181, v144, v145
	global_store_dwordx4 v[204:205], v[178:181], off sc1
.LBB0_1103:
	v_mov_b32_e32 v210, v208
	v_mov_b32_e32 v211, v208
	v_mov_b32_e32 v209, v208
	v_lshlrev_b32_e32 v178, 16, v174
	v_and_b32_e32 v179, 0xffff0000, v174
	v_lshlrev_b32_e32 v174, 16, v175
	v_and_b32_e32 v175, 0xffff0000, v175
	v_pk_mul_f32 v[140:141], v[140:141], v[210:211]
	v_lshlrev_b32_e32 v180, 16, v176
	v_and_b32_e32 v181, 0xffff0000, v176
	v_lshlrev_b32_e32 v176, 16, v177
	v_and_b32_e32 v177, 0xffff0000, v177
	v_pk_mul_f32 v[138:139], v[138:139], v[208:209]
	v_pk_fma_f32 v[140:141], v[104:105], v[140:141], v[174:175]
	v_pk_mul_f32 v[136:137], v[136:137], v[210:211]
	v_pk_mul_f32 v[134:135], v[134:135], v[208:209]
	v_cndmask_b32_e64 v174, 0, 1, s[30:31]
	v_pk_fma_f32 v[138:139], v[102:103], v[138:139], v[178:179]
	v_pk_fma_f32 v[136:137], v[96:97], v[136:137], v[176:177]
	v_cmp_ne_u32_e64 s[10:11], 1, v174
	s_andn2_b64 vcc, exec, s[30:31]
	v_pk_fma_f32 v[134:135], v[94:95], v[134:135], v[180:181]
	s_cbranch_vccnz .LBB0_1170
	global_store_dwordx4 v[206:207], v[138:141], off offset:512 sc1
	global_store_dwordx4 v[206:207], v[134:137], off offset:528 sc1
	s_cbranch_execnz .LBB0_1106
.LBB0_1105:
	v_cvt_pk_bf16_f32 v174, v138, v139
	v_cvt_pk_bf16_f32 v175, v140, v141
	v_cvt_pk_bf16_f32 v176, v134, v135
	v_cvt_pk_bf16_f32 v177, v136, v137
	global_store_dwordx4 v[204:205], v[174:177], off offset:256 sc1

.LBB0_1108:
	s_or_b64 exec, exec, s[30:31]
	v_lshl_add_u32 v134, v220, 2, s64
	ds_read_b32 v136, v134
	v_add_u32_e32 v138, s44, v220
	v_ashrrev_i32_e32 v139, 31, v138
	s_waitcnt lgkmcnt(1)
	v_lshlrev_b64 v[134:135], 10, v[138:139]
	v_lshl_add_u64 v[134:135], v[134:135], 0, v[196:197]
	v_lshlrev_b32_e32 v140, 16, v170
	v_and_b32_e32 v141, 0xffff0000, v170
	v_lshlrev_b32_e32 v142, 16, v171
	v_and_b32_e32 v143, 0xffff0000, v171
	v_lshlrev_b32_e32 v144, 16, v172
	v_and_b32_e32 v145, 0xffff0000, v172
	v_lshlrev_b32_e32 v146, 16, v173
	v_and_b32_e32 v147, 0xffff0000, v173
	s_waitcnt lgkmcnt(0)
	v_pk_mul_f32 v[132:133], v[132:133], v[136:137] op_sel_hi:[1,0]
	v_pk_mul_f32 v[130:131], v[130:131], v[136:137] op_sel_hi:[1,0]
	v_pk_mul_f32 v[128:129], v[128:129], v[136:137] op_sel_hi:[1,0]
	v_pk_mul_f32 v[126:127], v[126:127], v[136:137] op_sel_hi:[1,0]
	v_lshl_add_u64 v[134:135], v[134:135], 2, s[26:27]
	v_pk_fma_f32 v[132:133], v[116:117], v[132:133], v[142:143]
	v_pk_fma_f32 v[130:131], v[114:115], v[130:131], v[140:141]
	v_pk_fma_f32 v[128:129], v[112:113], v[128:129], v[146:147]
	s_and_b64 vcc, exec, s[10:11]
	v_pk_fma_f32 v[126:127], v[110:111], v[126:127], v[144:145]
	s_cbranch_vccnz .LBB0_1171
	global_store_dwordx4 v[134:135], v[130:133], off sc1
	global_store_dwordx4 v[134:135], v[126:129], off offset:16 sc1
	v_lshlrev_b64 v[138:139], 11, v[138:139]
	v_lshl_add_u64 v[138:139], v[200:201], 0, v[138:139]
	s_cbranch_execnz .LBB0_1111
.LBB0_1110:
	v_cvt_pk_bf16_f32 v140, v130, v131
	v_cvt_pk_bf16_f32 v141, v132, v133
	v_cvt_pk_bf16_f32 v142, v126, v127
	v_cvt_pk_bf16_f32 v143, v128, v129
	global_store_dwordx4 v[138:139], v[140:143], off sc1
.LBB0_1111:
	v_mov_b32_e32 v137, v136
	v_mov_b32_e32 v148, v136
	v_mov_b32_e32 v149, v136
	v_lshlrev_b32_e32 v140, 16, v166
	v_and_b32_e32 v141, 0xffff0000, v166
	v_lshlrev_b32_e32 v142, 16, v167
	v_and_b32_e32 v143, 0xffff0000, v167
	v_lshlrev_b32_e32 v144, 16, v168
	v_and_b32_e32 v145, 0xffff0000, v168
	v_lshlrev_b32_e32 v146, 16, v169
	v_and_b32_e32 v147, 0xffff0000, v169
	v_pk_mul_f32 v[124:125], v[124:125], v[148:149]
	v_pk_mul_f32 v[122:123], v[122:123], v[136:137]
	v_pk_mul_f32 v[120:121], v[120:121], v[148:149]
	v_pk_mul_f32 v[118:119], v[118:119], v[136:137]
	v_pk_fma_f32 v[124:125], v[104:105], v[124:125], v[142:143]
	v_pk_fma_f32 v[122:123], v[102:103], v[122:123], v[140:141]
	v_pk_fma_f32 v[120:121], v[96:97], v[120:121], v[146:147]
	s_and_b64 vcc, exec, s[10:11]
	v_pk_fma_f32 v[118:119], v[94:95], v[118:119], v[144:145]
	s_cbranch_vccnz .LBB0_1172
	global_store_dwordx4 v[134:135], v[122:125], off offset:512 sc1
	global_store_dwordx4 v[134:135], v[118:121], off offset:528 sc1
	s_cbranch_execnz .LBB0_1114
.LBB0_1113:
	v_cvt_pk_bf16_f32 v134, v122, v123
	v_cvt_pk_bf16_f32 v135, v124, v125
	v_cvt_pk_bf16_f32 v136, v118, v119
	v_cvt_pk_bf16_f32 v137, v120, v121
	global_store_dwordx4 v[138:139], v[134:137], off offset:256 sc1

.LBB0_1116:
	s_or_b64 exec, exec, s[30:31]
	v_lshl_add_u32 v118, v221, 2, s64
	ds_read_b32 v120, v118
	v_add_u32_e32 v122, s44, v221
	v_ashrrev_i32_e32 v123, 31, v122
	s_waitcnt lgkmcnt(1)
	v_lshlrev_b64 v[118:119], 10, v[122:123]
	v_lshl_add_u64 v[118:119], v[118:119], 0, v[196:197]
	v_lshlrev_b32_e32 v124, 16, v162
	v_and_b32_e32 v125, 0xffff0000, v162
	v_lshlrev_b32_e32 v126, 16, v163
	v_and_b32_e32 v127, 0xffff0000, v163
	v_lshlrev_b32_e32 v128, 16, v164
	v_and_b32_e32 v129, 0xffff0000, v164
	v_lshlrev_b32_e32 v130, 16, v165
	v_and_b32_e32 v131, 0xffff0000, v165
	s_waitcnt lgkmcnt(0)
	v_pk_mul_f32 v[108:109], v[108:109], v[120:121] op_sel_hi:[1,0]
	v_pk_mul_f32 v[106:107], v[106:107], v[120:121] op_sel_hi:[1,0]
	v_pk_mul_f32 v[100:101], v[100:101], v[120:121] op_sel_hi:[1,0]
	v_pk_mul_f32 v[98:99], v[98:99], v[120:121] op_sel_hi:[1,0]
	v_lshl_add_u64 v[118:119], v[118:119], 2, s[26:27]
	v_pk_fma_f32 v[108:109], v[116:117], v[108:109], v[126:127]
	v_pk_fma_f32 v[106:107], v[114:115], v[106:107], v[124:125]
	v_pk_fma_f32 v[100:101], v[112:113], v[100:101], v[130:131]
	s_and_b64 vcc, exec, s[10:11]
	v_pk_fma_f32 v[98:99], v[110:111], v[98:99], v[128:129]
	s_cbranch_vccnz .LBB0_1173
	global_store_dwordx4 v[118:119], v[106:109], off sc1
	global_store_dwordx4 v[118:119], v[98:101], off offset:16 sc1
	v_lshlrev_b64 v[122:123], 11, v[122:123]
	v_lshl_add_u64 v[122:123], v[200:201], 0, v[122:123]
	s_cbranch_execnz .LBB0_1119
.LBB0_1118:
	v_cvt_pk_bf16_f32 v124, v106, v107
	v_cvt_pk_bf16_f32 v125, v108, v109
	v_cvt_pk_bf16_f32 v126, v98, v99
	v_cvt_pk_bf16_f32 v127, v100, v101
	global_store_dwordx4 v[122:123], v[124:127], off sc1
.LBB0_1119:
	v_mov_b32_e32 v121, v120
	v_mov_b32_e32 v132, v120
	v_mov_b32_e32 v133, v120
	v_lshlrev_b32_e32 v124, 16, v158
	v_and_b32_e32 v125, 0xffff0000, v158
	v_lshlrev_b32_e32 v126, 16, v159
	v_and_b32_e32 v127, 0xffff0000, v159
	v_lshlrev_b32_e32 v128, 16, v160
	v_and_b32_e32 v129, 0xffff0000, v160
	v_lshlrev_b32_e32 v130, 16, v161
	v_and_b32_e32 v131, 0xffff0000, v161
	v_pk_mul_f32 v[92:93], v[92:93], v[132:133]
	v_pk_mul_f32 v[90:91], v[90:91], v[120:121]
	v_pk_mul_f32 v[88:89], v[88:89], v[132:133]
	v_pk_mul_f32 v[86:87], v[86:87], v[120:121]
	v_pk_fma_f32 v[92:93], v[104:105], v[92:93], v[126:127]
	v_pk_fma_f32 v[90:91], v[102:103], v[90:91], v[124:125]
	v_pk_fma_f32 v[88:89], v[96:97], v[88:89], v[130:131]
	s_and_b64 vcc, exec, s[10:11]
	v_pk_fma_f32 v[86:87], v[94:95], v[86:87], v[128:129]
	s_cbranch_vccnz .LBB0_1174
	global_store_dwordx4 v[118:119], v[90:93], off offset:512 sc1
	global_store_dwordx4 v[118:119], v[86:89], off offset:528 sc1
	s_cbranch_execnz .LBB0_1122
.LBB0_1121:
	v_cvt_pk_bf16_f32 v118, v90, v91
	v_cvt_pk_bf16_f32 v119, v92, v93
	v_cvt_pk_bf16_f32 v120, v86, v87
	v_cvt_pk_bf16_f32 v121, v88, v89
	global_store_dwordx4 v[122:123], v[118:121], off offset:256 sc1

.LBB0_1124:
	s_or_b64 exec, exec, s[30:31]
	v_lshl_add_u32 v86, v222, 2, s64
	ds_read_b32 v88, v86
	v_add_u32_e32 v90, s44, v222
	v_ashrrev_i32_e32 v91, 31, v90
	s_waitcnt lgkmcnt(1)
	v_lshlrev_b64 v[86:87], 10, v[90:91]
	v_lshl_add_u64 v[86:87], v[86:87], 0, v[196:197]
	v_lshlrev_b32_e32 v92, 16, v154
	v_and_b32_e32 v93, 0xffff0000, v154
	v_lshlrev_b32_e32 v98, 16, v155
	v_and_b32_e32 v99, 0xffff0000, v155
	v_lshlrev_b32_e32 v100, 16, v156
	v_and_b32_e32 v101, 0xffff0000, v156
	v_lshlrev_b32_e32 v106, 16, v157
	v_and_b32_e32 v107, 0xffff0000, v157
	s_waitcnt lgkmcnt(0)
	v_pk_mul_f32 v[84:85], v[84:85], v[88:89] op_sel_hi:[1,0]
	v_pk_mul_f32 v[82:83], v[82:83], v[88:89] op_sel_hi:[1,0]
	v_pk_mul_f32 v[80:81], v[80:81], v[88:89] op_sel_hi:[1,0]
	v_pk_mul_f32 v[78:79], v[78:79], v[88:89] op_sel_hi:[1,0]
	v_lshl_add_u64 v[86:87], v[86:87], 2, s[26:27]
	v_pk_fma_f32 v[84:85], v[116:117], v[84:85], v[98:99]
	v_pk_fma_f32 v[82:83], v[114:115], v[82:83], v[92:93]
	v_pk_fma_f32 v[80:81], v[112:113], v[80:81], v[106:107]
	s_and_b64 vcc, exec, s[10:11]
	v_pk_fma_f32 v[78:79], v[110:111], v[78:79], v[100:101]
	s_cbranch_vccnz .LBB0_1175
	global_store_dwordx4 v[86:87], v[82:85], off sc1
	global_store_dwordx4 v[86:87], v[78:81], off offset:16 sc1
	v_lshlrev_b64 v[90:91], 11, v[90:91]
	v_lshl_add_u64 v[90:91], v[200:201], 0, v[90:91]
	s_cbranch_execnz .LBB0_1127
.LBB0_1126:
	v_cvt_pk_bf16_f32 v98, v82, v83
	v_cvt_pk_bf16_f32 v99, v84, v85
	v_cvt_pk_bf16_f32 v100, v78, v79
	v_cvt_pk_bf16_f32 v101, v80, v81
	global_store_dwordx4 v[90:91], v[98:101], off sc1
.LBB0_1127:
	v_mov_b32_e32 v89, v88
	v_mov_b32_e32 v108, v88
	v_mov_b32_e32 v109, v88
	v_lshlrev_b32_e32 v92, 16, v150
	v_and_b32_e32 v93, 0xffff0000, v150
	v_lshlrev_b32_e32 v98, 16, v151
	v_and_b32_e32 v99, 0xffff0000, v151
	v_lshlrev_b32_e32 v100, 16, v152
	v_and_b32_e32 v101, 0xffff0000, v152
	v_lshlrev_b32_e32 v106, 16, v153
	v_and_b32_e32 v107, 0xffff0000, v153
	v_pk_mul_f32 v[76:77], v[76:77], v[108:109]
	v_pk_mul_f32 v[74:75], v[74:75], v[88:89]
	v_pk_mul_f32 v[72:73], v[72:73], v[108:109]
	v_pk_mul_f32 v[70:71], v[70:71], v[88:89]
	v_pk_fma_f32 v[76:77], v[104:105], v[76:77], v[98:99]
	v_pk_fma_f32 v[74:75], v[102:103], v[74:75], v[92:93]
	v_pk_fma_f32 v[72:73], v[96:97], v[72:73], v[106:107]
	s_and_b64 vcc, exec, s[10:11]
	v_pk_fma_f32 v[70:71], v[94:95], v[70:71], v[100:101]
	s_cbranch_vccnz .LBB0_1176
	global_store_dwordx4 v[86:87], v[74:77], off offset:512 sc1
	global_store_dwordx4 v[86:87], v[70:73], off offset:528 sc1
	s_cbranch_execnz .LBB0_1130
.LBB0_1129:
	v_cvt_pk_bf16_f32 v86, v74, v75
	v_cvt_pk_bf16_f32 v87, v76, v77
	v_cvt_pk_bf16_f32 v88, v70, v71
	v_cvt_pk_bf16_f32 v89, v72, v73
	global_store_dwordx4 v[90:91], v[86:89], off offset:256 sc1

.LBB0_1132:
	s_or_b64 exec, exec, s[30:31]
	s_waitcnt lgkmcnt(0)
	v_lshlrev_b64 v[70:71], 11, v[202:203]
	v_lshl_add_u64 v[106:107], v[200:201], 0, v[70:71]
	s_mov_b64 s[30:31], 0x40000
	v_add_co_u32_e32 v72, vcc, 0x48000, v106
	v_lshl_add_u64 v[70:71], v[106:107], 0, s[30:31]
	s_mov_b64 s[30:31], 0x48000
	v_addc_co_u32_e32 v73, vcc, 0, v107, vcc
	global_load_dwordx4 v[98:101], v[70:71], off offset:256
	v_lshl_add_u64 v[70:71], v[106:107], 0, s[30:31]
	global_load_dwordx4 v[90:93], v[72:73], off
	global_load_dwordx4 v[86:89], v[70:71], off offset:256
	v_add_co_u32_e32 v72, vcc, 0x50000, v106
	s_mov_b64 s[30:31], 0x50000
	s_nop 0
	v_addc_co_u32_e32 v73, vcc, 0, v107, vcc
	v_lshl_add_u64 v[70:71], v[106:107], 0, s[30:31]
	global_load_dwordx4 v[82:85], v[72:73], off
	global_load_dwordx4 v[78:81], v[70:71], off offset:256
	v_add_co_u32_e32 v72, vcc, 0x58000, v106
	s_mov_b64 s[30:31], 0x58000
	s_nop 0
	v_addc_co_u32_e32 v73, vcc, 0, v107, vcc
	v_lshl_add_u64 v[70:71], v[106:107], 0, s[30:31]
	v_add_co_u32_e32 v106, vcc, 0x40000, v106
	global_load_dwordx4 v[74:77], v[72:73], off
	s_nop 0
	global_load_dwordx4 v[70:73], v[70:71], off offset:256
	v_addc_co_u32_e32 v107, vcc, 0, v107, vcc
	global_load_dwordx4 v[120:123], v[106:107], off
	v_lshl_add_u32 v106, v223, 2, s64
	ds_read_b32 v106, v106
	v_add_u32_e32 v118, s44, v223
	v_ashrrev_i32_e32 v119, 31, v118
	v_lshlrev_b64 v[108:109], 10, v[118:119]
	v_lshl_add_u64 v[108:109], v[108:109], 0, v[196:197]
	s_waitcnt lgkmcnt(0)
	v_pk_mul_f32 v[68:69], v[68:69], v[106:107] op_sel_hi:[1,0]
	v_pk_mul_f32 v[66:67], v[66:67], v[106:107] op_sel_hi:[1,0]
	v_pk_mul_f32 v[64:65], v[64:65], v[106:107] op_sel_hi:[1,0]
	v_pk_mul_f32 v[62:63], v[62:63], v[106:107] op_sel_hi:[1,0]
	v_lshl_add_u64 v[108:109], v[108:109], 2, s[26:27]
	s_and_b64 vcc, exec, s[10:11]
	s_waitcnt vmcnt(0)
	v_lshlrev_b32_e32 v124, 16, v120
	v_and_b32_e32 v125, 0xffff0000, v120
	v_lshlrev_b32_e32 v120, 16, v121
	v_and_b32_e32 v121, 0xffff0000, v121
	v_lshlrev_b32_e32 v126, 16, v122
	v_and_b32_e32 v127, 0xffff0000, v122
	v_lshlrev_b32_e32 v122, 16, v123
	v_and_b32_e32 v123, 0xffff0000, v123
	v_pk_fma_f32 v[68:69], v[116:117], v[68:69], v[120:121]
	v_pk_fma_f32 v[66:67], v[114:115], v[66:67], v[124:125]
	v_pk_fma_f32 v[64:65], v[112:113], v[64:65], v[122:123]
	v_pk_fma_f32 v[62:63], v[110:111], v[62:63], v[126:127]
	s_cbranch_vccnz .LBB0_1177
	global_store_dwordx4 v[108:109], v[66:69], off sc1
	global_store_dwordx4 v[108:109], v[62:65], off offset:16 sc1
	v_lshlrev_b64 v[118:119], 11, v[118:119]
	v_lshl_add_u64 v[118:119], v[200:201], 0, v[118:119]
	s_cbranch_execnz .LBB0_1135
.LBB0_1134:
	v_cvt_pk_bf16_f32 v120, v66, v67
	v_cvt_pk_bf16_f32 v121, v68, v69
	v_cvt_pk_bf16_f32 v122, v62, v63
	v_cvt_pk_bf16_f32 v123, v64, v65
	global_store_dwordx4 v[118:119], v[120:123], off sc1
.LBB0_1135:
	v_mov_b32_e32 v107, v106
	v_mov_b32_e32 v124, v106
	v_mov_b32_e32 v125, v106
	v_lshlrev_b32_e32 v120, 16, v98
	v_and_b32_e32 v121, 0xffff0000, v98
	v_lshlrev_b32_e32 v98, 16, v99
	v_and_b32_e32 v99, 0xffff0000, v99
	v_lshlrev_b32_e32 v122, 16, v100
	v_and_b32_e32 v123, 0xffff0000, v100
	v_lshlrev_b32_e32 v100, 16, v101
	v_and_b32_e32 v101, 0xffff0000, v101
	v_pk_mul_f32 v[60:61], v[60:61], v[124:125]
	v_pk_mul_f32 v[58:59], v[58:59], v[106:107]
	v_pk_mul_f32 v[56:57], v[56:57], v[124:125]
	v_pk_mul_f32 v[54:55], v[54:55], v[106:107]
	v_pk_fma_f32 v[60:61], v[104:105], v[60:61], v[98:99]
	v_pk_fma_f32 v[58:59], v[102:103], v[58:59], v[120:121]
	v_pk_fma_f32 v[56:57], v[96:97], v[56:57], v[100:101]
	s_and_b64 vcc, exec, s[10:11]
	v_pk_fma_f32 v[54:55], v[94:95], v[54:55], v[122:123]
	s_cbranch_vccnz .LBB0_1178
	global_store_dwordx4 v[108:109], v[58:61], off offset:512 sc1
	global_store_dwordx4 v[108:109], v[54:57], off offset:528 sc1
	s_cbranch_execnz .LBB0_1138
.LBB0_1137:
	v_cvt_pk_bf16_f32 v98, v58, v59
	v_cvt_pk_bf16_f32 v99, v60, v61
	v_cvt_pk_bf16_f32 v100, v54, v55
	v_cvt_pk_bf16_f32 v101, v56, v57
	global_store_dwordx4 v[118:119], v[98:101], off offset:256 sc1

.LBB0_1140:
	s_or_b64 exec, exec, s[30:31]
	v_lshl_add_u32 v54, v224, 2, s64
	ds_read_b32 v56, v54
	v_add_u32_e32 v58, s44, v224
	v_ashrrev_i32_e32 v59, 31, v58
	s_waitcnt lgkmcnt(1)
	v_lshlrev_b64 v[54:55], 10, v[58:59]
	v_lshl_add_u64 v[54:55], v[54:55], 0, v[196:197]
	v_lshlrev_b32_e32 v60, 16, v90
	v_and_b32_e32 v61, 0xffff0000, v90
	v_lshlrev_b32_e32 v62, 16, v91
	v_and_b32_e32 v63, 0xffff0000, v91
	v_lshlrev_b32_e32 v64, 16, v92
	v_and_b32_e32 v65, 0xffff0000, v92
	v_lshlrev_b32_e32 v66, 16, v93
	v_and_b32_e32 v67, 0xffff0000, v93
	s_waitcnt lgkmcnt(0)
	v_pk_mul_f32 v[52:53], v[52:53], v[56:57] op_sel_hi:[1,0]
	v_pk_mul_f32 v[50:51], v[50:51], v[56:57] op_sel_hi:[1,0]
	v_pk_mul_f32 v[48:49], v[48:49], v[56:57] op_sel_hi:[1,0]
	v_pk_mul_f32 v[46:47], v[46:47], v[56:57] op_sel_hi:[1,0]
	v_lshl_add_u64 v[54:55], v[54:55], 2, s[26:27]
	v_pk_fma_f32 v[52:53], v[116:117], v[52:53], v[62:63]
	v_pk_fma_f32 v[50:51], v[114:115], v[50:51], v[60:61]
	v_pk_fma_f32 v[48:49], v[112:113], v[48:49], v[66:67]
	s_and_b64 vcc, exec, s[10:11]
	v_pk_fma_f32 v[46:47], v[110:111], v[46:47], v[64:65]
	s_cbranch_vccnz .LBB0_1179
	global_store_dwordx4 v[54:55], v[50:53], off sc1
	global_store_dwordx4 v[54:55], v[46:49], off offset:16 sc1
	v_lshlrev_b64 v[58:59], 11, v[58:59]
	v_lshl_add_u64 v[58:59], v[200:201], 0, v[58:59]
	s_cbranch_execnz .LBB0_1143
.LBB0_1142:
	v_cvt_pk_bf16_f32 v60, v50, v51
	v_cvt_pk_bf16_f32 v61, v52, v53
	v_cvt_pk_bf16_f32 v62, v46, v47
	v_cvt_pk_bf16_f32 v63, v48, v49
	global_store_dwordx4 v[58:59], v[60:63], off sc1
.LBB0_1143:
	v_mov_b32_e32 v57, v56
	v_mov_b32_e32 v68, v56
	v_mov_b32_e32 v69, v56
	v_lshlrev_b32_e32 v60, 16, v86
	v_and_b32_e32 v61, 0xffff0000, v86
	v_lshlrev_b32_e32 v62, 16, v87
	v_and_b32_e32 v63, 0xffff0000, v87
	v_lshlrev_b32_e32 v64, 16, v88
	v_and_b32_e32 v65, 0xffff0000, v88
	v_lshlrev_b32_e32 v66, 16, v89
	v_and_b32_e32 v67, 0xffff0000, v89
	v_pk_mul_f32 v[44:45], v[44:45], v[68:69]
	v_pk_mul_f32 v[42:43], v[42:43], v[56:57]
	v_pk_mul_f32 v[40:41], v[40:41], v[68:69]
	v_pk_mul_f32 v[38:39], v[38:39], v[56:57]
	v_pk_fma_f32 v[44:45], v[104:105], v[44:45], v[62:63]
	v_pk_fma_f32 v[42:43], v[102:103], v[42:43], v[60:61]
	v_pk_fma_f32 v[40:41], v[96:97], v[40:41], v[66:67]
	s_and_b64 vcc, exec, s[10:11]
	v_pk_fma_f32 v[38:39], v[94:95], v[38:39], v[64:65]
	s_cbranch_vccnz .LBB0_1180
	global_store_dwordx4 v[54:55], v[42:45], off offset:512 sc1
	global_store_dwordx4 v[54:55], v[38:41], off offset:528 sc1
	s_cbranch_execnz .LBB0_1146
.LBB0_1145:
	v_cvt_pk_bf16_f32 v54, v42, v43
	v_cvt_pk_bf16_f32 v55, v44, v45
	v_cvt_pk_bf16_f32 v56, v38, v39
	v_cvt_pk_bf16_f32 v57, v40, v41
	global_store_dwordx4 v[58:59], v[54:57], off offset:256 sc1

.LBB0_1148:
	s_or_b64 exec, exec, s[30:31]
	v_lshl_add_u32 v38, v225, 2, s64
	ds_read_b32 v40, v38
	v_add_u32_e32 v42, s44, v225
	v_ashrrev_i32_e32 v43, 31, v42
	s_waitcnt lgkmcnt(1)
	v_lshlrev_b64 v[38:39], 10, v[42:43]
	v_lshl_add_u64 v[38:39], v[38:39], 0, v[196:197]
	v_lshlrev_b32_e32 v44, 16, v82
	v_and_b32_e32 v45, 0xffff0000, v82
	v_lshlrev_b32_e32 v46, 16, v83
	v_and_b32_e32 v47, 0xffff0000, v83
	v_lshlrev_b32_e32 v48, 16, v84
	v_and_b32_e32 v49, 0xffff0000, v84
	v_lshlrev_b32_e32 v50, 16, v85
	v_and_b32_e32 v51, 0xffff0000, v85
	s_waitcnt lgkmcnt(0)
	v_pk_mul_f32 v[36:37], v[36:37], v[40:41] op_sel_hi:[1,0]
	v_pk_mul_f32 v[34:35], v[34:35], v[40:41] op_sel_hi:[1,0]
	v_pk_mul_f32 v[32:33], v[32:33], v[40:41] op_sel_hi:[1,0]
	v_pk_mul_f32 v[30:31], v[30:31], v[40:41] op_sel_hi:[1,0]
	v_lshl_add_u64 v[38:39], v[38:39], 2, s[26:27]
	v_pk_fma_f32 v[36:37], v[116:117], v[36:37], v[46:47]
	v_pk_fma_f32 v[34:35], v[114:115], v[34:35], v[44:45]
	v_pk_fma_f32 v[32:33], v[112:113], v[32:33], v[50:51]
	s_and_b64 vcc, exec, s[10:11]
	v_pk_fma_f32 v[30:31], v[110:111], v[30:31], v[48:49]
	s_cbranch_vccnz .LBB0_1181
	global_store_dwordx4 v[38:39], v[34:37], off sc1
	global_store_dwordx4 v[38:39], v[30:33], off offset:16 sc1
	v_lshlrev_b64 v[42:43], 11, v[42:43]
	v_lshl_add_u64 v[42:43], v[200:201], 0, v[42:43]
	s_cbranch_execnz .LBB0_1151
.LBB0_1150:
	v_cvt_pk_bf16_f32 v44, v34, v35
	v_cvt_pk_bf16_f32 v45, v36, v37
	v_cvt_pk_bf16_f32 v46, v30, v31
	v_cvt_pk_bf16_f32 v47, v32, v33
	global_store_dwordx4 v[42:43], v[44:47], off sc1
.LBB0_1151:
	v_mov_b32_e32 v41, v40
	v_mov_b32_e32 v52, v40
	v_mov_b32_e32 v53, v40
	v_lshlrev_b32_e32 v44, 16, v78
	v_and_b32_e32 v45, 0xffff0000, v78
	v_lshlrev_b32_e32 v46, 16, v79
	v_and_b32_e32 v47, 0xffff0000, v79
	v_lshlrev_b32_e32 v48, 16, v80
	v_and_b32_e32 v49, 0xffff0000, v80
	v_lshlrev_b32_e32 v50, 16, v81
	v_and_b32_e32 v51, 0xffff0000, v81
	v_pk_mul_f32 v[28:29], v[28:29], v[52:53]
	v_pk_mul_f32 v[26:27], v[26:27], v[40:41]
	v_pk_mul_f32 v[24:25], v[24:25], v[52:53]
	v_pk_mul_f32 v[22:23], v[22:23], v[40:41]
	v_pk_fma_f32 v[28:29], v[104:105], v[28:29], v[46:47]
	v_pk_fma_f32 v[26:27], v[102:103], v[26:27], v[44:45]
	v_pk_fma_f32 v[24:25], v[96:97], v[24:25], v[50:51]
	s_and_b64 vcc, exec, s[10:11]
	v_pk_fma_f32 v[22:23], v[94:95], v[22:23], v[48:49]
	s_cbranch_vccnz .LBB0_1182
	global_store_dwordx4 v[38:39], v[26:29], off offset:512 sc1
	global_store_dwordx4 v[38:39], v[22:25], off offset:528 sc1
	s_cbranch_execnz .LBB0_1154
.LBB0_1153:
	v_cvt_pk_bf16_f32 v38, v26, v27
	v_cvt_pk_bf16_f32 v39, v28, v29
	v_cvt_pk_bf16_f32 v40, v22, v23
	v_cvt_pk_bf16_f32 v41, v24, v25
	global_store_dwordx4 v[42:43], v[38:41], off offset:256 sc1

.LBB0_1156:
	s_or_b64 exec, exec, s[30:31]
	v_lshl_add_u32 v22, v226, 2, s64
	ds_read_b32 v24, v22
	v_add_u32_e32 v26, s44, v226
	v_ashrrev_i32_e32 v27, 31, v26
	s_waitcnt lgkmcnt(1)
	v_lshlrev_b64 v[22:23], 10, v[26:27]
	v_lshl_add_u64 v[22:23], v[22:23], 0, v[196:197]
	v_lshlrev_b32_e32 v28, 16, v74
	v_and_b32_e32 v29, 0xffff0000, v74
	v_lshlrev_b32_e32 v30, 16, v75
	v_and_b32_e32 v31, 0xffff0000, v75
	v_lshlrev_b32_e32 v32, 16, v76
	v_and_b32_e32 v33, 0xffff0000, v76
	v_lshlrev_b32_e32 v34, 16, v77
	v_and_b32_e32 v35, 0xffff0000, v77
	s_waitcnt lgkmcnt(0)
	v_pk_mul_f32 v[20:21], v[20:21], v[24:25] op_sel_hi:[1,0]
	v_pk_mul_f32 v[18:19], v[18:19], v[24:25] op_sel_hi:[1,0]
	v_pk_mul_f32 v[16:17], v[16:17], v[24:25] op_sel_hi:[1,0]
	v_pk_mul_f32 v[14:15], v[14:15], v[24:25] op_sel_hi:[1,0]
	v_lshl_add_u64 v[22:23], v[22:23], 2, s[26:27]
	v_pk_fma_f32 v[20:21], v[116:117], v[20:21], v[30:31]
	v_pk_fma_f32 v[18:19], v[114:115], v[18:19], v[28:29]
	v_pk_fma_f32 v[16:17], v[112:113], v[16:17], v[34:35]
	s_and_b64 vcc, exec, s[10:11]
	v_pk_fma_f32 v[14:15], v[110:111], v[14:15], v[32:33]
	s_cbranch_vccnz .LBB0_1183
	global_store_dwordx4 v[22:23], v[18:21], off sc1
	global_store_dwordx4 v[22:23], v[14:17], off offset:16 sc1
	v_lshlrev_b64 v[26:27], 11, v[26:27]
	v_lshl_add_u64 v[26:27], v[200:201], 0, v[26:27]
	s_cbranch_execnz .LBB0_1159
.LBB0_1158:
	v_cvt_pk_bf16_f32 v28, v18, v19
	v_cvt_pk_bf16_f32 v29, v20, v21
	v_cvt_pk_bf16_f32 v30, v14, v15
	v_cvt_pk_bf16_f32 v31, v16, v17
	global_store_dwordx4 v[26:27], v[28:31], off sc1
.LBB0_1159:
	v_mov_b32_e32 v25, v24
	v_mov_b32_e32 v36, v24
	v_mov_b32_e32 v37, v24
	v_lshlrev_b32_e32 v28, 16, v70
	v_and_b32_e32 v29, 0xffff0000, v70
	v_lshlrev_b32_e32 v30, 16, v71
	v_and_b32_e32 v31, 0xffff0000, v71
	v_lshlrev_b32_e32 v32, 16, v72
	v_and_b32_e32 v33, 0xffff0000, v72
	v_lshlrev_b32_e32 v34, 16, v73
	v_and_b32_e32 v35, 0xffff0000, v73
	v_pk_mul_f32 v[12:13], v[12:13], v[36:37]
	v_pk_mul_f32 v[10:11], v[10:11], v[24:25]
	v_pk_mul_f32 v[8:9], v[8:9], v[36:37]
	v_pk_mul_f32 v[6:7], v[6:7], v[24:25]
	v_pk_fma_f32 v[12:13], v[104:105], v[12:13], v[30:31]
	v_pk_fma_f32 v[10:11], v[102:103], v[10:11], v[28:29]
	v_pk_fma_f32 v[8:9], v[96:97], v[8:9], v[34:35]
	s_and_b64 vcc, exec, s[10:11]
	v_pk_fma_f32 v[6:7], v[94:95], v[6:7], v[32:33]
	s_cbranch_vccnz .LBB0_1184
	global_store_dwordx4 v[22:23], v[10:13], off offset:512 sc1
	global_store_dwordx4 v[22:23], v[6:9], off offset:528 sc1
	s_cbranch_execnz .LBB0_1162
.LBB0_1161:
	v_cvt_pk_bf16_f32 v22, v10, v11
	v_cvt_pk_bf16_f32 v23, v12, v13
	v_cvt_pk_bf16_f32 v24, v6, v7
	v_cvt_pk_bf16_f32 v25, v8, v9
	global_store_dwordx4 v[26:27], v[22:25], off offset:256 sc1
